# conv phase: weight/state base pointers fetched by s_load of both kernarg slots + per-lane select instead of a vector load round trip
# baseline (speedup 1.0000x reference)
; __device__ __forceinline__ const float* pin(int i) { return kargs()->in[i]; }
; __device__ __forceinline__ void phase_conv(const Params& p, int l, const XcdBarrier& xbar) {
;     ...
;     const bool ssd = cgi >= 96; const int ch = (ssd ? cgi - 96 : cgi) * 8;
;     const int col = (ssd ? C_SXBC : C_GQKV) + ch;
;     const float* cw = (ssd ? pin(16) : pin(12)) + (size_t)l * 4 * 768 + ch;
;     float w[4][8], bias[8];
; #pragma unroll
;     for (int j = 0; j < 4; ++j) { const f32x4 a = *(const f32x4*)(cw + j * 768), b = *(const f32x4*)(cw + j * 768 + 4);
; #pragma unroll
;         for (int e = 0; e < 4; ++e) { w[j][e] = a[e]; w[j][e + 4] = b[e]; } }
; #pragma unroll
;     for (int e = 0; e < 8; ++e) bias[e] = ssd ? pin(17)[l * 768 + ch + e] : 0.f;
.LBB0_434:
	s_or_b64 exec, exec, s[6:7]
	s_load_dwordx2 s[8:9], s[0:1], 0x60
	s_load_dwordx2 s[2:3], s[0:1], 0x80
	s_waitcnt lgkmcnt(0)
	v_mov_b32_e32 v0, s2
	v_mov_b32_e32 v1, s3
	v_mov_b32_e32 v16, s8
	v_mov_b32_e32 v38, s9
	v_cndmask_b32_e64 v0, v0, v16, s[50:51]
	v_cndmask_b32_e64 v1, v1, v38, s[50:51]
	v_lshlrev_b32_e32 v16, 3, v2
	s_and_b64 s[2:3], s[58:59], exec
	v_add_u32_e32 v38, 0xfffffd00, v16
	s_cselect_b32 s78, 0x3000, 0
	v_cndmask_b32_e64 v148, v16, v38, s[42:43]
	v_ashrrev_i32_e32 v149, 31, v148
	s_mov_b64 s[2:3], 0x1800
	v_mov_b32_e32 v147, 0
	v_mov_b32_e32 v146, 0
	s_waitcnt vmcnt(0)
	v_lshl_add_u64 v[0:1], v[0:1], 0, s[78:79]
	v_lshl_add_u64 v[12:13], v[148:149], 2, v[0:1]
	v_lshl_add_u64 v[8:9], v[12:13], 0, s[2:3]
	s_movk_i32 s2, 0x1000
	v_add_co_u32_e32 v10, vcc, s2, v12
	s_mov_b64 s[2:3], 0x2400
	s_nop 0
	v_addc_co_u32_e32 v11, vcc, 0, v13, vcc
	global_load_dwordx4 v[0:3], v[12:13], off offset:16
	global_load_dwordx4 v[22:25], v[12:13], off
	global_load_dwordx4 v[4:7], v[12:13], off offset:3088
	global_load_dwordx4 v[26:29], v[12:13], off offset:3072
	v_lshl_add_u64 v[14:15], v[12:13], 0, s[2:3]
	v_add_co_u32_e32 v12, vcc, 0x2000, v12
	global_load_dwordx4 v[30:33], v[10:11], off offset:2048
	s_nop 0
	global_load_dwordx4 v[8:11], v[8:9], off offset:16
	v_addc_co_u32_e32 v13, vcc, 0, v13, vcc
	global_load_dwordx4 v[34:37], v[12:13], off offset:1024
	global_load_dwordx4 v[18:21], v[14:15], off offset:16
	v_cndmask_b32_e64 v12, v38, v16, s[58:59]
	v_ashrrev_i32_e32 v13, 31, v12
	s_and_saveexec_b64 s[6:7], s[42:43]
	s_cbranch_execz .LBB0_436
	s_mov_b64 s[2:3], s[0:1]
	s_load_dwordx2 s[2:3], s[2:3], 0x88
	s_waitcnt lgkmcnt(0)
	v_lshl_add_u64 v[14:15], v[12:13], 2, s[2:3]
	global_load_dword v146, v[14:15], off

; __device__ __forceinline__ const float* pin(int i) { return kargs()->in[i]; }
; __device__ __forceinline__ void phase_conv(const Params& p, int l, const XcdBarrier& xbar) {
;     ...
;     else if (kind == 1) { const float* st = (ssd ? pin(7) : pin(4)) + (size_t)((l * NSB + unit) * 3) * 768 + ch;
; #pragma unroll
;         for (int i = 0; i < 3; ++i) { const f32x4 a = *(const f32x4*)(st + i * 768), b = *(const f32x4*)(st + i * 768 + 4);
;             h[i] = (u32x4){pkh(a[0], a[1]), pkh(a[2], a[3]), pkh(b[0], b[1]), pkh(b[2], b[3])}; } }
.LBB0_460:
	s_or_b64 exec, exec, s[10:11]
	s_load_dwordx2 s[12:13], s[0:1], 32
	s_load_dwordx2 s[2:3], s[0:1], 56
	s_waitcnt lgkmcnt(0)
	v_mov_b32_e32 v12, s2
	v_mov_b32_e32 v13, s3
	v_mov_b32_e32 v14, s12
	v_mov_b32_e32 v16, s13
	v_cndmask_b32_e64 v12, v12, v14, s[50:51]
	v_cndmask_b32_e64 v13, v13, v16, s[50:51]
	s_and_b64 s[2:3], s[58:59], exec
	s_cselect_b32 s2, 0x80, 0
	v_add_u32_e32 v14, s2, v78
	s_movk_i32 s2, 0x2400
	v_mul_lo_u32 v16, v14, s2
	s_mov_b64 s[2:3], 0x1800
	s_waitcnt vmcnt(0)
	v_lshl_add_u64 v[12:13], v[12:13], 0, v[16:17]
	v_lshl_add_u64 v[44:45], v[148:149], 2, v[12:13]
	v_lshl_add_u64 v[48:49], v[44:45], 0, s[2:3]
	global_load_dwordx4 v[12:15], v[44:45], off
	global_load_dwordx4 v[38:41], v[44:45], off offset:16
	global_load_dwordx4 v[54:57], v[44:45], off offset:3072
	global_load_dwordx4 v[58:61], v[44:45], off offset:3088
	global_load_dwordx4 v[62:65], v[48:49], off offset:16
	global_load_dwordx4 v[42:45], v[48:49], off
	s_movk_i32 s2, 0x1000
	s_waitcnt vmcnt(4)
	v_cvt_pk_f16_f32 v12, v12, v13
	v_cvt_pk_f16_f32 v13, v14, v15
	v_cvt_pk_f16_f32 v14, v38, v39
	v_cvt_pk_f16_f32 v15, v40, v41
	s_waitcnt vmcnt(2)
	v_cvt_pk_f16_f32 v38, v54, v55
	v_cvt_pk_f16_f32 v39, v56, v57
	v_cvt_pk_f16_f32 v40, v58, v59
	v_cvt_pk_f16_f32 v41, v60, v61
	s_waitcnt vmcnt(0)
	v_cvt_pk_f16_f32 v42, v42, v43
	v_cvt_pk_f16_f32 v43, v44, v45
	v_cvt_pk_f16_f32 v44, v62, v63
	v_cvt_pk_f16_f32 v45, v64, v65
